# prompt-attention main loop: first QK MFMA of the step moved directly behind the loop-back barrier, ahead of the P-pack conversions (MFMA-first segment head)
# baseline (speedup 1.0000x reference)
; #define WAIT_BAR(N) asm volatile("s_waitcnt vmcnt(" #N ") lgkmcnt(0)\n\ts_barrier":::"memory")
; template<int THRL> __device__ __forceinline__ void attn_unit(int b,int h,int qb,const bf16*Q,const bf16*__restrict__ K,const bf16*__restrict__ V,bf16*O,char*shm,lds_cfptr bt,const int wid_in){
;     ...
;   WAIT_BAR(3);
;   kload8(kf,kp0);
.LBB0_378:
	v_ashrrev_i32_e32 v200, 4, v198
	v_lshlrev_b32_e32 v80, 5, v200
	v_lshlrev_b32_e32 v81, 8, v217
	v_lshlrev_b32_e32 v82, 4, v198
	s_addk_i32 s40, 0x6000
	v_and_b32_e32 v80, 32, v80
	v_and_b32_e32 v82, 0xc0, v82
	v_add3_u32 v81, v81, s40, v136
	v_add3_u32 v199, v81, v82, v80
	s_mov_b32 s42, 1
	s_andn2_b64 vcc, exec, s[4:5]
	v_cmp_gt_u32_e64 s[4:5], 32, v198
	s_cbranch_vccnz .LBB0_395
	v_lshlrev_b32_e32 v214, 2, v217
	v_add_u32_e32 v81, s77, v214
	v_sub_u32_e32 v81, v81, v201
	s_lshl_b32 s34, s90, 6
	v_lshlrev_b32_e32 v80, 4, v217
	v_subrev_u32_e32 v219, s34, v81
	s_add_i32 s34, s78, s34
	s_add_i32 s43, s90, -7
	v_lshl_add_u32 v218, v201, 2, s74
	v_sub_u32_e32 v220, s34, v214
	s_sub_i32 s48, 0, s90
	s_movk_i32 s94, 0x4000
	s_movk_i32 s50, 0x2000
	s_mov_b64 s[40:41], 0
	s_mov_b32 s49, 0x10000
	v_add_u32_e32 v221, s74, v80
	s_waitcnt lgkmcnt(7)
	v_mfma_f32_32x32x16_bf16 v[96:111], v[184:187], v[156:159], v[64:79]
	s_branch .LBB0_381
.LBB0_380:
	s_add_i32 s42, s42, 2
	s_add_i32 s34, s50, 0x2000
	s_cmpk_lg_i32 s50, 0x4000
	s_waitcnt vmcnt(3) lgkmcnt(0)
	s_barrier
	v_mfma_f32_32x32x16_bf16 v[96:111], v[184:187], v[156:159], v[64:79]
	s_cselect_b32 s94, s34, 0
	s_add_u32 s40, s40, 0x40000
	v_add_f32_e32 v80, v84, v85
	s_addc_u32 s41, s41, 0
	s_add_i32 s49, s49, 0x8000
	v_add_f32_e32 v203, v192, v80
	v_cvt_pk_bf16_f32 v192, v128, v129
	v_cvt_pk_bf16_f32 v193, v130, v131
	v_cvt_pk_bf16_f32 v194, v132, v133
	v_cvt_pk_bf16_f32 v195, v134, v135
	v_cvt_pk_bf16_f32 v132, v136, v137
	v_cvt_pk_bf16_f32 v133, v138, v139
	v_cvt_pk_bf16_f32 v134, v140, v141
	v_cvt_pk_bf16_f32 v135, v142, v143
	v_cvt_pk_bf16_f32 v128, v112, v113
	v_cvt_pk_bf16_f32 v129, v114, v115
	v_cvt_pk_bf16_f32 v130, v116, v117
	v_cvt_pk_bf16_f32 v131, v118, v119
	v_cvt_pk_bf16_f32 v112, v120, v121
	v_cvt_pk_bf16_f32 v113, v122, v123
	v_cvt_pk_bf16_f32 v114, v124, v125
	v_cvt_pk_bf16_f32 v115, v126, v127
	v_add_u32_e32 v219, 0x80, v219
	s_cmp_ge_i32 s42, s43
	v_add_u32_e32 v220, 0xffffff80, v220
	s_cbranch_scc1 .LBB0_396
.LBB0_381:
	s_add_i32 s34, s50, s55
	v_lshl_add_u64 v[210:211], v[208:209], 0, s[40:41]
	v_add_u32_e32 v120, s94, v216
	s_waitcnt lgkmcnt(6)
	v_mfma_f32_32x32x16_bf16 v[80:95], v[188:191], v[156:159], v[64:79]
	v_lshl_add_u64 v[188:189], v[204:205], 0, s[40:41]
	v_lshl_add_u64 v[116:117], v[188:189], 0, s[26:27]
	s_mov_b32 s44, m0
	s_mov_b32 m0, s34
	s_nop 0
	global_load_lds_dwordx4 v[116:117], off
	s_mov_b32 m0, s44
	s_add_i32 s34, s49, 0xffffc000
	v_lshl_add_u64 v[190:191], v[206:207], 0, s[40:41]
	s_and_b32 s34, s34, 0xc000
	v_lshl_add_u64 v[116:117], v[190:191], 0, s[24:25]
	s_waitcnt lgkmcnt(5)
	v_mfma_f32_32x32x16_bf16 v[96:111], v[180:183], v[152:155], v[96:111]
	s_add_i32 s34, s34, s56
	s_mov_b32 s44, m0
	s_mov_b32 m0, s34
	s_nop 0
	global_load_lds_dwordx4 v[116:117], off
	s_mov_b32 m0, s44
	v_lshl_add_u64 v[116:117], v[210:211], 0, s[24:25]
	s_addk_i32 s34, 0x2000
	s_mov_b32 s44, m0
	s_mov_b32 m0, s34
	s_nop 0
	global_load_lds_dwordx4 v[116:117], off
	s_mov_b32 m0, s44
	s_waitcnt lgkmcnt(4)
	v_mfma_f32_32x32x16_bf16 v[80:95], v[176:179], v[152:155], v[80:95]
	s_waitcnt lgkmcnt(3)
	v_mfma_f32_32x32x16_bf16 v[96:111], v[172:175], v[148:151], v[96:111]
	s_waitcnt lgkmcnt(2)
	v_mfma_f32_32x32x16_bf16 v[80:95], v[168:171], v[148:151], v[80:95]
	s_waitcnt lgkmcnt(1)
	v_mfma_f32_32x32x16_bf16 v[96:111], v[164:167], v[144:147], v[96:111]
	s_waitcnt lgkmcnt(0)
	v_mfma_f32_32x32x16_bf16 v[80:95], v[160:163], v[144:147], v[80:95]
	ds_read_b128 v[116:119], v120
	ds_read_b128 v[184:187], v120 offset:512
	ds_read_b128 v[180:183], v120 offset:2048
	ds_read_b128 v[176:179], v120 offset:2560
	ds_read_b128 v[160:163], v120 offset:4096
	ds_read_b128 v[164:167], v120 offset:4608
	ds_read_b128 v[168:171], v120 offset:6144
	ds_read_b128 v[172:175], v120 offset:6656
